# attention: Q-fragment register sets alternate between jobs (loads and QK MFMAs selected by job parity), removing the 16-move copy in each job's first step
# speedup vs baseline: 1.0002x; 1.0002x over previous
; __device__ __forceinline__ void attn_chain(LAS unsigned char* lds, const bf16* Qb, const bf16* Kb, const bf16* Vb, bf16* Ob, float* lseb, int g0, int wave, int lane) {
;     ...
;         if (act && t == 0) {
;             asm volatile("" : "+v"(qn[0]), "+v"(qn[1]), "+v"(qn[2]), "+v"(qn[3]), "+v"(qn[4]), "+v"(qn[5]), "+v"(qn[6]), "+v"(qn[7]));
; #pragma unroll
;             for (int s2 = 0; s2 < 8; ++s2) qf[s2] = qn[s2];
;         }
;         __builtin_amdgcn_s_barrier();
;         asm volatile("" ::: "memory");
;         { int k0, k1 = -1;
;           if (ph == 0) k0 = 8 * mm + 4; else if (ph == 1) { k0 = 8 * mm + 5; k1 = k0 + 1; } else if (ph == 2) k0 = 8 * mm + 7; else if (ph == 3) { k0 = 8 * mm + 8; k1 = k0 + 1; } else { k0 = 8 * mm + 10; k1 = k0 + 1; }
;           p1 = 0;
;           if (k0 < NKB) { AC_ISSUE(k0); p1 = 2; }
;           if (k1 >= 0 && k1 < NKB) { AC_ISSUE(k1); p1 += 2; } }
.LBB0_669:
	s_cmp_eq_u32 s3, 0
	s_cselect_b64 s[72:73], -1, 0
	s_and_b64 s[12:13], s[6:7], s[72:73]
	s_andn2_b64 vcc, exec, s[12:13]
	s_cbranch_vccnz .LBB0_671
	s_nop 0
.LBB0_671:
	s_barrier
	s_mul_i32 s100, s14, 0xfffec000
	s_add_i32 s100, s82, s100
	s_and_b32 s100, s100, 0x1c000
	v_add_u32_e32 v216, s100, v158
	v_xad_u32 v217, v216, 16, 0
	ds_read_b128 v[220:223], v216
	ds_read_b128 v[170:173], v217
	v_xad_u32 v217, v216, 32, 0
	v_xad_u32 v218, v216, 48, 0
	ds_read_b128 v[178:181], v217
	ds_read_b128 v[184:187], v218
	v_xad_u32 v217, v216, 64, 0
	v_xor_b32_e32 v218, 0x50, v216
	ds_read_b128 v[188:191], v217
	ds_read_b128 v[192:195], v218
	v_xor_b32_e32 v217, 0x60, v216
	v_xor_b32_e32 v218, 0x70, v216
	ds_read_b128 v[196:199], v217
	ds_read_b128 v[200:203], v218
	s_lshl_b32 s42, s85, 3
	s_lshl_b32 s12, s86, 2
	s_lshr_b32 s40, 0xa8754, s12
	s_and_b32 s40, s40, 15
	s_add_i32 s40, s40, s42
	s_lshr_b32 s12, 26, s86
	s_and_b32 s12, s12, 1
	s_add_i32 s33, s40, 1
	s_cmp_eq_u32 s12, 0
	s_cselect_b32 s33, -1, s33

; #define AC_QLOAD(n_) do { const int gq_ = g0 + wave + 8 * (n_); AC_MAP(gq_, pq_, dq_, rq_, lq_); \
;     const bf16* qp_ = Qb + (size_t)(rq_ + dq_ * (32 * lq_ + r32)) * 1024 + 64 * hi; \
;     _Pragma("unroll") for (int s_ = 0; s_ < 8; ++s_) asm volatile("global_load_dwordx4 %0, %1, off" : "=v"(qn[s_]) : "v"(qp_ + 8 * s_) : "memory"); } while (0)
; __device__ __forceinline__ void attn_chain(LAS unsigned char* lds, const bf16* Qb, const bf16* Kb, const bf16* Vb, bf16* Ob, float* lseb, int g0, int wave, int lane) {
;     ...
;         if (act && t == 3 && n + 1 < NJOB) AC_QLOAD(n + 1);
.LBB0_689:
	s_cmp_eq_u32 s3, 3
	s_cselect_b64 s[12:13], -1, 0
	s_and_b64 s[12:13], s[6:7], s[12:13]
	s_cmp_lt_u32 s14, 5
	s_cselect_b64 s[42:43], -1, 0
	s_and_b64 s[12:13], s[12:13], s[42:43]
	s_andn2_b64 vcc, exec, s[12:13]
	s_cbranch_vccnz .LBB0_691
	s_lshl_b32 s3, s2, 3
	s_add_i32 s3, s67, s3
	s_lshr_b32 s12, s3, 6
	s_and_b32 s12, s12, 0x7ffffe
	s_sub_i32 s13, 7, s12
	s_and_b32 s31, s3, 0x7f
	s_lshr_b32 s31, s31, s13
	s_lshl_b32 s13, -1, s13
	s_andn2_b32 s3, s3, s13
	v_lshl_or_b32 v64, s3, 5, v157
	v_lshlrev_b32_e32 v64, s12, v64
	v_add_u32_e32 v64, s31, v64
	v_ashrrev_i32_e32 v65, 31, v64
	v_lshlrev_b64 v[64:65], 11, v[64:65]
	v_lshl_add_u64 v[64:65], v[154:155], 0, v[64:65]
	s_bitcmp1_b32 s14, 0
	s_cbranch_scc0 .Lattn_q_to_a
	global_load_dwordx4 v[80:83], v[64:65], off
	v_lshl_add_u64 v[66:67], v[64:65], 0, 16
	global_load_dwordx4 v[84:87], v[66:67], off
	v_lshl_add_u64 v[66:67], v[64:65], 0, 32
	global_load_dwordx4 v[88:91], v[66:67], off
	v_lshl_add_u64 v[66:67], v[64:65], 0, 48
	global_load_dwordx4 v[92:95], v[66:67], off
	v_lshl_add_u64 v[66:67], v[64:65], 0, 64
	global_load_dwordx4 v[96:99], v[66:67], off
	v_lshl_add_u64 v[66:67], v[64:65], 0, s[44:45]
	global_load_dwordx4 v[100:103], v[66:67], off
	v_lshl_add_u64 v[66:67], v[64:65], 0, s[46:47]
	global_load_dwordx4 v[104:107], v[66:67], off
	v_lshl_add_u64 v[64:65], v[64:65], 0, s[48:49]
	global_load_dwordx4 v[108:111], v[64:65], off
	s_branch .Lattn_q_done
.Lattn_q_to_a:
	global_load_dwordx4 v[112:115], v[64:65], off
	v_lshl_add_u64 v[66:67], v[64:65], 0, 16
	global_load_dwordx4 v[116:119], v[66:67], off
	v_lshl_add_u64 v[66:67], v[64:65], 0, 32
	global_load_dwordx4 v[120:123], v[66:67], off
	v_lshl_add_u64 v[66:67], v[64:65], 0, 48
	global_load_dwordx4 v[124:127], v[66:67], off
	v_lshl_add_u64 v[66:67], v[64:65], 0, 64
	global_load_dwordx4 v[128:131], v[66:67], off
	v_lshl_add_u64 v[66:67], v[64:65], 0, s[44:45]
	global_load_dwordx4 v[132:135], v[66:67], off
	v_lshl_add_u64 v[66:67], v[64:65], 0, s[46:47]
	global_load_dwordx4 v[136:139], v[66:67], off
	v_lshl_add_u64 v[64:65], v[64:65], 0, s[48:49]
	global_load_dwordx4 v[140:143], v[64:65], off
.Lattn_q_done:
.LBB0_691:
	s_andn2_b64 vcc, exec, s[6:7]
	s_cbranch_vccnz .LBB0_642
	s_and_b64 s[6:7], s[70:71], s[72:73]
	s_andn2_b64 vcc, exec, s[6:7]
	s_lshl_b32 s2, s2, 3
	s_cbranch_vccnz .LBB0_696
	s_add_i32 s3, s80, s2
	v_mov_b32_e32 v64, v182
	s_nop 1
	v_permlane32_swap_b32_e32 v64, v182
	s_nop 1
	s_ashr_i32 s6, s3, 7
	s_lshl_b32 s7, s6, 1
	s_sub_i32 s12, 7, s7
	s_and_b32 s13, s3, 0x7f
	s_lshr_b32 s31, s13, s12
	s_lshl_b32 s12, -1, s12
	s_waitcnt lgkmcnt(0)
	v_add_f32_e32 v66, v182, v64
	s_andn2_b32 s3, s3, s12
	v_div_scale_f32 v65, s[12:13], v66, v66, 1.0
	v_rcp_f32_e32 v67, v65
	v_lshl_or_b32 v64, s3, 5, v157
	v_lshlrev_b32_e32 v64, s7, v64
	s_ashr_i32 s7, s6, 31
	v_fma_f32 v68, -v65, v67, 1.0
	v_fmac_f32_e32 v67, v68, v67
	v_div_scale_f32 v68, vcc, 1.0, v66, 1.0
	v_mul_f32_e32 v69, v68, v67
	v_fma_f32 v70, -v65, v69, v68
	v_fmac_f32_e32 v69, v70, v67
	v_fma_f32 v65, -v65, v69, v68
	v_div_fmas_f32 v65, v65, v67, v69
	v_add_u32_e32 v64, s31, v64
	v_div_fixup_f32 v68, v65, v66, 1.0
	s_lshl_b64 s[12:13], s[6:7], 25
	s_add_u32 s12, s28, s12
	v_ashrrev_i32_e32 v65, 31, v64
	v_pk_mul_f32 v[48:49], v[48:49], v[68:69] op_sel_hi:[1,0]
	v_pk_mul_f32 v[50:51], v[50:51], v[68:69] op_sel_hi:[1,0]
	v_pk_mul_f32 v[32:33], v[32:33], v[68:69] op_sel_hi:[1,0]
	v_pk_mul_f32 v[34:35], v[34:35], v[68:69] op_sel_hi:[1,0]
	v_pk_mul_f32 v[16:17], v[16:17], v[68:69] op_sel_hi:[1,0]
	v_pk_mul_f32 v[18:19], v[18:19], v[68:69] op_sel_hi:[1,0]
	v_pk_mul_f32 v[0:1], v[0:1], v[68:69] op_sel_hi:[1,0]
	v_pk_mul_f32 v[2:3], v[2:3], v[68:69] op_sel_hi:[1,0]
	s_addc_u32 s13, s57, s13
	v_lshlrev_b64 v[70:71], 11, v[64:65]
	v_cvt_pk_bf16_f32 v48, v48, v49
	v_cvt_pk_bf16_f32 v49, v50, v51
	v_pk_mul_f32 v[50:51], v[52:53], v[68:69] op_sel_hi:[1,0]
	v_pk_mul_f32 v[52:53], v[54:55], v[68:69] op_sel_hi:[1,0]
	v_cvt_pk_bf16_f32 v32, v32, v33
	v_cvt_pk_bf16_f32 v33, v34, v35
	v_pk_mul_f32 v[34:35], v[36:37], v[68:69] op_sel_hi:[1,0]
	v_pk_mul_f32 v[36:37], v[38:39], v[68:69] op_sel_hi:[1,0]
	v_cvt_pk_bf16_f32 v16, v16, v17
	v_cvt_pk_bf16_f32 v17, v18, v19
	v_pk_mul_f32 v[18:19], v[20:21], v[68:69] op_sel_hi:[1,0]
	v_pk_mul_f32 v[20:21], v[22:23], v[68:69] op_sel_hi:[1,0]
	v_cvt_pk_bf16_f32 v0, v0, v1
	v_cvt_pk_bf16_f32 v1, v2, v3
	v_pk_mul_f32 v[2:3], v[4:5], v[68:69] op_sel_hi:[1,0]
	v_pk_mul_f32 v[4:5], v[6:7], v[68:69] op_sel_hi:[1,0]
	v_lshl_add_u64 v[70:71], s[12:13], 0, v[70:71]
	v_cvt_pk_bf16_f32 v50, v50, v51
	v_cvt_pk_bf16_f32 v51, v52, v53
	v_cvt_pk_bf16_f32 v34, v34, v35
	v_cvt_pk_bf16_f32 v35, v36, v37
	v_cvt_pk_bf16_f32 v18, v18, v19
	v_cvt_pk_bf16_f32 v19, v20, v21
	v_cvt_pk_bf16_f32 v2, v2, v3
	v_cvt_pk_bf16_f32 v3, v4, v5
	v_lshl_add_u64 v[70:71], v[144:145], 1, v[70:71]
	v_permlane32_swap_b32_e32 v48, v50
	v_permlane32_swap_b32_e32 v49, v51
	v_permlane32_swap_b32_e32 v32, v34
	v_permlane32_swap_b32_e32 v33, v35
	v_permlane32_swap_b32_e32 v16, v18
	v_permlane32_swap_b32_e32 v17, v19
	v_permlane32_swap_b32_e32 v0, v2
	v_permlane32_swap_b32_e32 v1, v3
	global_store_dwordx4 v[70:71], v[48:51], off
	global_store_dwordx4 v[70:71], v[32:35], off offset:64
	global_store_dwordx4 v[70:71], v[16:19], off offset:128
	v_pk_mul_f32 v[48:49], v[56:57], v[68:69] op_sel_hi:[1,0]
	v_pk_mul_f32 v[50:51], v[58:59], v[68:69] op_sel_hi:[1,0]
	v_pk_mul_f32 v[32:33], v[40:41], v[68:69] op_sel_hi:[1,0]
	v_pk_mul_f32 v[34:35], v[42:43], v[68:69] op_sel_hi:[1,0]
	v_pk_mul_f32 v[16:17], v[24:25], v[68:69] op_sel_hi:[1,0]
	v_pk_mul_f32 v[18:19], v[26:27], v[68:69] op_sel_hi:[1,0]
	global_store_dwordx4 v[70:71], v[0:3], off offset:192
	v_cvt_pk_bf16_f32 v48, v48, v49
	v_cvt_pk_bf16_f32 v49, v50, v51
	v_pk_mul_f32 v[0:1], v[8:9], v[68:69] op_sel_hi:[1,0]
	v_pk_mul_f32 v[2:3], v[10:11], v[68:69] op_sel_hi:[1,0]
	v_pk_mul_f32 v[50:51], v[60:61], v[68:69] op_sel_hi:[1,0]
	v_pk_mul_f32 v[52:53], v[62:63], v[68:69] op_sel_hi:[1,0]
	v_cvt_pk_bf16_f32 v32, v32, v33
	v_cvt_pk_bf16_f32 v33, v34, v35
	v_pk_mul_f32 v[34:35], v[44:45], v[68:69] op_sel_hi:[1,0]
	v_pk_mul_f32 v[36:37], v[46:47], v[68:69] op_sel_hi:[1,0]
	v_cvt_pk_bf16_f32 v16, v16, v17
	v_cvt_pk_bf16_f32 v17, v18, v19
	v_pk_mul_f32 v[18:19], v[28:29], v[68:69] op_sel_hi:[1,0]
	v_pk_mul_f32 v[20:21], v[30:31], v[68:69] op_sel_hi:[1,0]
	v_cvt_pk_bf16_f32 v0, v0, v1
	v_cvt_pk_bf16_f32 v1, v2, v3
	v_pk_mul_f32 v[2:3], v[12:13], v[68:69] op_sel_hi:[1,0]
	v_pk_mul_f32 v[4:5], v[14:15], v[68:69] op_sel_hi:[1,0]
	v_cvt_pk_bf16_f32 v50, v50, v51
	v_cvt_pk_bf16_f32 v51, v52, v53
	v_cvt_pk_bf16_f32 v34, v34, v35
	v_cvt_pk_bf16_f32 v35, v36, v37
	v_cvt_pk_bf16_f32 v18, v18, v19
	v_cvt_pk_bf16_f32 v19, v20, v21
	v_cvt_pk_bf16_f32 v2, v2, v3
	v_cvt_pk_bf16_f32 v3, v4, v5
	v_permlane32_swap_b32_e32 v48, v50
	v_permlane32_swap_b32_e32 v49, v51
	v_permlane32_swap_b32_e32 v32, v34
	v_permlane32_swap_b32_e32 v33, v35
	v_permlane32_swap_b32_e32 v16, v18
	v_permlane32_swap_b32_e32 v17, v19
	v_permlane32_swap_b32_e32 v0, v2
	v_permlane32_swap_b32_e32 v1, v3
	global_store_dwordx4 v[70:71], v[48:51], off offset:32
	global_store_dwordx4 v[70:71], v[32:35], off offset:96
	global_store_dwordx4 v[70:71], v[16:19], off offset:160
	global_store_dwordx4 v[70:71], v[0:3], off offset:224
	s_and_saveexec_b64 s[70:71], s[4:5]
	s_cbranch_execz .LBB0_695
	v_cmp_gt_f32_e32 vcc, s93, v66
	s_lshl_b64 s[6:7], s[6:7], 19
	s_add_u32 s6, s22, s6
	v_cndmask_b32_e64 v0, 0, 32, vcc
	v_ldexp_f32 v0, v66, v0
	v_log_f32_e32 v2, v0
	v_cndmask_b32_e32 v3, 0, v236, vcc
	s_addc_u32 s7, s23, s7
	v_lshlrev_b64 v[0:1], 5, v[64:65]
	v_sub_f32_e32 v2, v2, v3
	v_lshl_add_u64 v[0:1], s[6:7], 0, v[0:1]
	v_add_f32_e32 v2, v149, v2
	global_store_dword v[0:1], v2, off

; #define LAS __attribute__((address_space(3)))
; __device__ __forceinline__ void attn_chain(LAS unsigned char* lds, const bf16* Qb, const bf16* Kb, const bf16* Vb, bf16* Ob, float* lseb, int g0, int wave, int lane) {
;     ...
;             const int L = wave + 8 * n, kk = L + t, gq = g0 + L, gk = gq - 2 + t;
;             AC_MAP(gq, pq, dq, rq, lq);
;             const bool valid = gk >= 0 && gk < 384 && (gk >> 7) == pq && (((gk & 127) >> shpq) == rq);
;             (void)dq; (void)lq;
;             if (valid) {
;                 const unsigned kb_ = kbl + (unsigned)(kk & 7) * 16384u;
;                 bf16x8 kf[8];
; #pragma unroll
;                 for (int s2 = 0; s2 < 8; ++s2) kf[s2] = *(const LAS bf16x8*)(lds + (kb_ ^ ((unsigned)s2 << 4)));
;                 f32x16 sa;
; #pragma unroll
;                 for (int i = 0; i < 16; ++i) sa[i] = 0.f;
;                 __builtin_amdgcn_sched_barrier(0); asm volatile("s_waitcnt lgkmcnt(0)" ::: "memory"); __builtin_amdgcn_sched_barrier(0);
; #pragma unroll
;                 for (int s2 = 0; s2 < 8; ++s2) sa = __builtin_amdgcn_mfma_f32_32x32x16_bf16(kf[s2], qf[s2], sa, 0, 0, 0);
.LBB0_696:
	s_and_b32 s3, s83, 0xff
	s_mul_hi_u32 s3, s3, 0x33333334
	s_lshl_b32 s3, s3, 3
	s_add_i32 s3, s59, s3
	s_add_i32 s2, s2, s66
	s_add_i32 s30, s30, s3
	s_lshr_b32 s3, s2, 7
	s_cmpk_gt_u32 s30, 0x17f
	s_cselect_b64 s[6:7], -1, 0
	s_lshr_b32 s12, s30, 7
	s_cmp_lg_u32 s12, s3
	s_cselect_b64 s[12:13], -1, 0
	s_or_b64 s[6:7], s[6:7], s[12:13]
	s_and_b64 vcc, exec, s[6:7]
	s_cbranch_vccnz .Lattn_invalid
	s_lshl_b32 s3, s3, 1
	s_and_b32 s2, s2, 0x7f
	s_sub_i32 s3, 7, s3
	s_and_b32 s6, s30, 0x7f
	s_lshr_b32 s2, s2, s3
	s_lshr_b32 s3, s6, s3
	s_cmp_lg_u32 s3, s2
	s_cbranch_scc1 .Lattn_invalid
	s_mul_i32 s2, s14, 0xfffec000
	s_add_i32 s2, s82, s2
	s_and_b32 s2, s2, 0x1c000
	s_waitcnt lgkmcnt(0)
	s_waitcnt lgkmcnt(0)
	s_bitcmp1_b32 s14, 0
	s_cbranch_scc0 .Lattn_qk_even
	v_mfma_f32_32x32x16_bf16 v[64:79], v[220:223], v[112:115], 0
	s_cmp_lt_i32 s15, 4
	v_mfma_f32_32x32x16_bf16 v[64:79], v[170:173], v[116:119], v[64:79]
	v_mfma_f32_32x32x16_bf16 v[64:79], v[178:181], v[120:123], v[64:79]
	v_mfma_f32_32x32x16_bf16 v[64:79], v[184:187], v[124:127], v[64:79]
	v_mfma_f32_32x32x16_bf16 v[64:79], v[188:191], v[128:131], v[64:79]
	v_mfma_f32_32x32x16_bf16 v[64:79], v[192:195], v[132:135], v[64:79]
	v_mfma_f32_32x32x16_bf16 v[64:79], v[196:199], v[136:139], v[64:79]
	v_mfma_f32_32x32x16_bf16 v[64:79], v[200:203], v[140:143], v[64:79]
	s_branch .Lattn_qk_done
.Lattn_qk_even:
	v_mfma_f32_32x32x16_bf16 v[64:79], v[220:223], v[80:83], 0
	s_cmp_lt_i32 s15, 4
	v_mfma_f32_32x32x16_bf16 v[64:79], v[170:173], v[84:87], v[64:79]
	v_mfma_f32_32x32x16_bf16 v[64:79], v[178:181], v[88:91], v[64:79]
	v_mfma_f32_32x32x16_bf16 v[64:79], v[184:187], v[92:95], v[64:79]
	v_mfma_f32_32x32x16_bf16 v[64:79], v[188:191], v[96:99], v[64:79]
	v_mfma_f32_32x32x16_bf16 v[64:79], v[192:195], v[100:103], v[64:79]
	v_mfma_f32_32x32x16_bf16 v[64:79], v[196:199], v[104:107], v[64:79]
	v_mfma_f32_32x32x16_bf16 v[64:79], v[200:203], v[108:111], v[64:79]
.Lattn_qk_done:
	s_cbranch_scc1 .LBB0_708
	s_cmp_eq_u32 s15, 4
	s_cselect_b64 s[6:7], -1, 0
	s_cbranch_execz .LBB0_709
	s_branch .LBB0_710
